# halves de-synchronised after layer 0: phase-4 conversion split unevenly, global barrier replaced by per-half barrier plus bounded cross-half generation wait
# speedup vs baseline: 1.0120x; 1.0120x over previous
_ZN2mk4megaENS_6ParamsE:
	s_lshr_b32 s97, s2, 7
	s_nop 0
	v_writelane_b32 v255, s97, 61
	s_mov_b64 s[66:67], s[0:1]
	s_load_dwordx2 s[0:1], s[0:1], 0xb0
	s_nop 0
	s_load_dword s13, s[66:67], 0xc0
	s_add_u32 s6, s66, 0xc0
	v_and_b32_e32 v247, 0x3ff, v0
	s_addc_u32 s7, s67, 0
	v_cmp_gt_u32_e32 vcc, 4, v247
	s_and_saveexec_b64 s[4:5], vcc
	v_lshl_add_u32 v1, v247, 2, 0
	v_add_u32_e32 v1, 0x23fc0, v1
	v_mov_b32_e32 v2, 0
	ds_write_b32 v1, v2
	s_or_b64 exec, exec, s[4:5]
	s_waitcnt lgkmcnt(0)
	s_add_u32 s0, s0, 0x8560000
	v_lshl_add_u32 v2, s2, 9, v247
	s_movk_i32 s3, 0x3000
	s_mov_b32 s33, s2
	s_mov_b32 s88, s2
	s_addc_u32 s1, s1, 0
	v_cmp_gt_i32_e32 vcc, s3, v2
	s_barrier
	s_and_saveexec_b64 s[4:5], vcc
	s_cbranch_execz .LBB0_5
	s_lshl_b32 s3, s13, 9
	s_mov_b64 s[8:9], 0
	v_mov_b32_e32 v1, 0
	s_movk_i32 s10, 0x2fff

.LBB0_151:
	s_cmp_eq_u32 s54, 4
	s_cbranch_scc1 .Lxw
	s_cmp_lg_u32 s54, 8
	s_cbranch_scc1 .Lxw_done
.Lxw:
	v_readfirstlane_b32 s100, v247
	s_nop 3
	s_cmp_ge_u32 s100, 64
	s_cbranch_scc1 .Lxw_join
	v_readlane_b32 s100, v255, 61
	s_load_dwordx2 s[98:99], s[66:67], 0xb0
	s_sub_i32 s101, 2, s100
	s_mul_i32 s101, s101, 0x3600
	s_add_i32 s101, s101, 0x8563500
	s_waitcnt lgkmcnt(0)
	s_add_u32 s98, s98, s101
	s_addc_u32 s99, s99, 0
	s_lshl_b32 s101, s100, 2
	s_add_i32 s101, s101, s54
	s_cmp_eq_u32 s101, 4
	s_cselect_b32 s101, 1, 4
	s_mov_b32 s100, 0x2000
.Lxw_poll:
	global_load_dword v0, v209, s[98:99] sc1
	s_waitcnt vmcnt(0)
	v_readfirstlane_b32 vcc_lo, v0
	s_nop 3
	s_cmp_ge_u32 vcc_lo, s101
	s_cbranch_scc1 .Lxw_got
	s_sleep 2
	s_sub_u32 s100, s100, 1
	s_cmp_lg_u32 s100, 0
	s_cbranch_scc1 .Lxw_poll
.Lxw_got:
	buffer_inv sc1
	s_waitcnt vmcnt(0)
.Lxw_join:
	s_barrier
.Lxw_done:
	s_add_i32 s54, s54, 1
	s_cmp_eq_u32 s54, 17
	s_cbranch_scc1 .LBB0_1056

.Lxbar_h:
	s_getreg_b32 s6, hwreg(HW_REG_XCC_ID, 0, 4)
	s_waitcnt vmcnt(0)
	s_waitcnt vmcnt(0) lgkmcnt(0)
	s_barrier
	s_and_saveexec_b64 s[4:5], s[68:69]
	s_cbranch_execz .LBB0_985
	v_readlane_b32 s7, v254, 3
	s_waitcnt vmcnt(0) expcnt(0) lgkmcnt(0)
	s_and_b32 s12, s6, 15
	v_mov_b32_e32 v0, s7
	ds_read_b32 v2, v0
	v_readlane_b32 s7, v254, 4
	s_waitcnt lgkmcnt(0)
	v_cmp_ne_u32_e32 vcc, 0, v2
	v_mov_b32_e32 v0, s7
	ds_read_b32 v0, v0
	s_cbranch_vccnz .LBB0_949
	s_mov_b32 s13, 1
	s_branch .LBB0_937

.Lph4_bar:
	s_mov_b64 s[2:3], 0
	s_branch .Lxbar_h
